# phase0 weight-transpose: 16 strided loads issued together (was 4 serialized groups); row0 h-stores deferred to iteration end; gdnpre item-top store drain removed
# speedup vs baseline: 1.0271x; 1.0029x over previous
.LBB0_35:
	s_or_b64 exec, exec, s[12:13]
	v_mov_b32_e32 v3, v0
	v_lshl_add_u64 v[2:3], v[4:5], 0, v[2:3]
	global_load_dwordx4 v[18:21], v[2:3], off nt
	global_load_dwordx4 v[10:13], v[2:3], off offset:1024 nt
	global_load_dwordx4 v[6:9], v[2:3], off offset:2048 nt
	s_nop 0
	global_load_dwordx4 v[2:5], v[2:3], off offset:3072 nt
	v_ashrrev_i32_e32 v45, 12, v52
	s_waitcnt vmcnt(7)
	v_mov_b32_e32 v62, v31
	s_waitcnt vmcnt(6)
	v_mov_b32_e32 v63, v27
	s_waitcnt vmcnt(5)
	v_mov_b32_e32 v70, v23
	s_waitcnt vmcnt(4)
	v_mov_b32_e32 v71, v15
	v_mov_b32_e32 v52, v30
	v_mov_b32_e32 v53, v26
	v_mov_b32_e32 v68, v22
	v_mov_b32_e32 v69, v14
	v_add_u32_e32 v96, 1, v45
	v_pk_mul_f32 v[62:63], v[62:63], v[62:63]
	v_pk_mul_f32 v[70:71], v[70:71], v[70:71]
	v_mov_b32_e32 v64, v32
	v_mov_b32_e32 v65, v28
	v_mov_b32_e32 v72, v24
	v_mov_b32_e32 v73, v16
	v_cndmask_b32_e64 v45, v96, 0, s[0:1]
	v_pk_fma_f32 v[52:53], v[52:53], v[52:53], v[62:63]
	v_pk_fma_f32 v[62:63], v[68:69], v[68:69], v[70:71]
	v_mov_b32_e32 v74, v25
	v_mov_b32_e32 v75, v17
	v_pk_fma_f32 v[52:53], v[64:65], v[64:65], v[52:53]
	v_pk_fma_f32 v[62:63], v[72:73], v[72:73], v[62:63]
	v_mul_hi_i32_i24_e32 v65, 0x3000, v45
	v_mul_i32_i24_e32 v64, 0x3000, v45
	v_pk_fma_f32 v[70:71], v[74:75], v[74:75], v[62:63]
	v_lshl_add_u64 v[62:63], s[30:31], 0, v[64:65]
	s_mov_b64 s[40:41], 0x1000
	v_mov_b32_e32 v66, v33
	v_mov_b32_e32 v67, v29
	v_mov_b32_e32 v43, v0
	v_lshl_add_u64 v[72:73], v[62:63], 0, s[40:41]
	v_pk_fma_f32 v[52:53], v[66:67], v[66:67], v[52:53]
	v_lshl_add_u64 v[74:75], v[62:63], 0, v[42:43]
	v_lshl_add_u64 v[66:67], v[72:73], 0, v[42:43]
	global_load_dwordx4 v[58:61], v[36:37], off
	global_load_dwordx4 v[62:65], v[74:75], off
	s_nop 0
	global_load_dwordx4 v[66:69], v[66:67], off
	v_mov_b32_e32 v77, v52
	v_mov_b32_e32 v79, v70
	s_mov_b32 s0, 0x3a800000
	s_mov_b32 s12, 0x800000
	v_mov_b32_e32 v45, v0
	v_mov_b32_e32 v49, v0
	s_add_i32 s43, s43, s2
	s_mov_b32 s98, 0x800000
	s_cmpk_gt_i32 s43, 0x13ff
	s_waitcnt vmcnt(6)
	v_mov_b32_e32 v82, v19
	s_waitcnt vmcnt(5)
	v_mov_b32_e32 v83, v11
	v_mov_b32_e32 v80, v18
	v_mov_b32_e32 v81, v10
	s_waitcnt vmcnt(4)
	v_mov_b32_e32 v90, v7
	s_waitcnt vmcnt(3)
	v_mov_b32_e32 v91, v3
	v_pk_mul_f32 v[82:83], v[82:83], v[82:83]
	v_mov_b32_e32 v84, v20
	v_mov_b32_e32 v85, v12
	v_mov_b32_e32 v88, v6
	v_mov_b32_e32 v89, v2
	v_pk_mul_f32 v[90:91], v[90:91], v[90:91]
	v_pk_fma_f32 v[80:81], v[80:81], v[80:81], v[82:83]
	v_mov_b32_e32 v86, v21
	v_mov_b32_e32 v87, v13
	v_mov_b32_e32 v92, v8
	v_mov_b32_e32 v93, v4
	v_pk_fma_f32 v[82:83], v[88:89], v[88:89], v[90:91]
	v_pk_fma_f32 v[80:81], v[84:85], v[84:85], v[80:81]
	v_mov_b32_e32 v94, v9
	v_mov_b32_e32 v95, v5
	v_pk_fma_f32 v[82:83], v[92:93], v[92:93], v[82:83]
	v_pk_fma_f32 v[80:81], v[86:87], v[86:87], v[80:81]
	v_pk_fma_f32 v[82:83], v[94:95], v[94:95], v[82:83]
	v_mov_b32_e32 v76, v80
	v_mov_b32_e32 v52, v81
	v_mov_b32_e32 v78, v82
	v_pk_add_f32 v[52:53], v[76:77], v[52:53]
	v_mov_b32_e32 v70, v83
	v_pk_add_f32 v[52:53], v[52:53], v[78:79]
	v_lshlrev_b64 v[76:77], 11, v[40:41]
	v_pk_add_f32 v[52:53], v[52:53], v[70:71]
	ds_bpermute_b32 v71, v1, v53
	ds_bpermute_b32 v70, v1, v52
	v_lshl_add_u64 v[76:77], v[38:39], 0, v[76:77]
	v_add_u32_e32 v40, s42, v40
	s_waitcnt lgkmcnt(0)
	v_pk_add_f32 v[52:53], v[52:53], v[70:71]
	ds_bpermute_b32 v71, v35, v53
	ds_bpermute_b32 v70, v35, v52
	s_waitcnt vmcnt(0)
	v_pk_add_f32 v[66:67], v[66:67], 1.0 op_sel_hi:[1,0]
	v_pk_add_f32 v[68:69], v[68:69], 1.0 op_sel_hi:[1,0]
	s_waitcnt lgkmcnt(0)
	v_pk_add_f32 v[52:53], v[52:53], v[70:71]
	ds_bpermute_b32 v71, v54, v53
	ds_bpermute_b32 v70, v54, v52
	s_waitcnt lgkmcnt(0)
	v_pk_add_f32 v[52:53], v[52:53], v[70:71]
	ds_bpermute_b32 v71, v55, v53
	ds_bpermute_b32 v70, v55, v52
	s_waitcnt lgkmcnt(0)
	v_pk_add_f32 v[52:53], v[52:53], v[70:71]
	ds_bpermute_b32 v71, v56, v53
	ds_bpermute_b32 v70, v56, v52
	s_waitcnt lgkmcnt(0)
	v_pk_add_f32 v[52:53], v[52:53], v[70:71]
	ds_bpermute_b32 v71, v57, v53
	ds_bpermute_b32 v70, v57, v52
	s_waitcnt lgkmcnt(0)
	v_pk_add_f32 v[52:53], v[52:53], v[70:71]
	s_nop 0
	v_pk_fma_f32 v[52:53], v[52:53], s[0:1], v[148:149] op_sel_hi:[1,0,0]
	v_lshl_add_u64 v[70:71], v[72:73], 0, v[44:45]
	v_mul_f32_e32 v41, 0x4b800000, v53
	v_cmp_gt_f32_e64 s[0:1], s12, v53
	s_nop 1
	v_cndmask_b32_e64 v41, v53, v41, s[0:1]
	v_rsq_f32_e32 v41, v41
	s_nop 0
	v_mul_f32_e32 v47, 0x45800000, v41
	v_cndmask_b32_e64 v78, v41, v47, s[0:1]
	v_pk_mul_f32 v[30:31], v[30:31], v[78:79] op_sel_hi:[1,0]
	v_pk_mul_f32 v[32:33], v[32:33], v[78:79] op_sel_hi:[1,0]
	v_pk_mul_f32 v[30:31], v[58:59], v[30:31]
	v_pk_mul_f32 v[32:33], v[60:61], v[32:33]
	v_pk_fma_f32 v[30:31], v[66:67], v[30:31], v[62:63]
	v_pk_fma_f32 v[32:33], v[32:33], v[68:69], v[64:65]
	v_cvt_pk_bf16_f32 v30, v30, v31
	v_cvt_pk_bf16_f32 v31, v32, v33
	v_mov_b32_e32 v152, v30
	v_mov_b32_e32 v153, v31
	global_load_dwordx4 v[30:33], v[36:37], off offset:1024
	s_nop 0
	global_load_dwordx4 v[58:61], v[70:71], off
	global_load_dwordx4 v[62:65], v[74:75], off offset:1024
	v_pk_mul_f32 v[26:27], v[26:27], v[78:79] op_sel_hi:[1,0]
	v_pk_mul_f32 v[28:29], v[28:29], v[78:79] op_sel_hi:[1,0]
	v_mov_b32_e32 v47, v0
	v_lshl_add_u64 v[66:67], v[72:73], 0, v[46:47]
	v_pk_mul_f32 v[22:23], v[22:23], v[78:79] op_sel_hi:[1,0]
	v_pk_mul_f32 v[24:25], v[24:25], v[78:79] op_sel_hi:[1,0]
	v_pk_mul_f32 v[14:15], v[14:15], v[78:79] op_sel_hi:[1,0]
	v_pk_mul_f32 v[16:17], v[16:17], v[78:79] op_sel_hi:[1,0]
	v_cndmask_b32_e64 v41, v96, 0, vcc
	v_cmp_gt_f32_e32 vcc, s12, v52
	s_waitcnt vmcnt(2)
	v_pk_mul_f32 v[26:27], v[26:27], v[30:31]
	s_waitcnt vmcnt(1)
	v_pk_add_f32 v[30:31], v[58:59], 1.0 op_sel_hi:[1,0]
	v_pk_mul_f32 v[28:29], v[28:29], v[32:33]
	v_pk_add_f32 v[32:33], v[60:61], 1.0 op_sel_hi:[1,0]
	s_waitcnt vmcnt(0)
	v_pk_fma_f32 v[26:27], v[26:27], v[30:31], v[62:63]
	v_pk_fma_f32 v[28:29], v[28:29], v[32:33], v[64:65]
	v_cvt_pk_bf16_f32 v26, v26, v27
	v_cvt_pk_bf16_f32 v27, v28, v29
	v_mov_b32_e32 v154, v26
	v_mov_b32_e32 v155, v27
	global_load_dwordx4 v[26:29], v[36:37], off offset:2048
	s_nop 0
	global_load_dwordx4 v[30:33], v[66:67], off
	global_load_dwordx4 v[58:61], v[74:75], off offset:2048
	v_lshl_add_u64 v[62:63], v[72:73], 0, v[48:49]
	s_waitcnt vmcnt(2)
	v_pk_mul_f32 v[22:23], v[22:23], v[26:27]
	s_waitcnt vmcnt(1)
	v_pk_add_f32 v[26:27], v[30:31], 1.0 op_sel_hi:[1,0]
	v_pk_mul_f32 v[24:25], v[24:25], v[28:29]
	v_pk_add_f32 v[28:29], v[32:33], 1.0 op_sel_hi:[1,0]
	s_waitcnt vmcnt(0)
	v_pk_fma_f32 v[22:23], v[22:23], v[26:27], v[58:59]
	v_pk_fma_f32 v[24:25], v[24:25], v[28:29], v[60:61]
	v_cvt_pk_bf16_f32 v22, v22, v23
	v_cvt_pk_bf16_f32 v23, v24, v25
	v_mov_b32_e32 v156, v22
	v_mov_b32_e32 v157, v23
	global_load_dwordx4 v[22:25], v[36:37], off offset:3072
	s_nop 0
	global_load_dwordx4 v[26:29], v[62:63], off
	global_load_dwordx4 v[30:33], v[74:75], off offset:3072
	v_mul_hi_i32_i24_e32 v59, 0x3000, v41
	v_mul_i32_i24_e32 v58, 0x3000, v41
	v_lshl_add_u64 v[58:59], s[30:31], 0, v[58:59]
	v_lshl_add_u64 v[60:61], v[58:59], 0, s[40:41]
	v_lshl_add_u64 v[62:63], v[60:61], 0, v[42:43]
	s_waitcnt vmcnt(2)
	v_pk_mul_f32 v[14:15], v[14:15], v[22:23]
	s_waitcnt vmcnt(1)
	v_pk_add_f32 v[22:23], v[26:27], 1.0 op_sel_hi:[1,0]
	v_pk_mul_f32 v[16:17], v[16:17], v[24:25]
	v_pk_add_f32 v[24:25], v[28:29], 1.0 op_sel_hi:[1,0]
	s_waitcnt vmcnt(0)
	v_pk_fma_f32 v[14:15], v[14:15], v[22:23], v[30:31]
	v_pk_fma_f32 v[16:17], v[16:17], v[24:25], v[32:33]
	v_cvt_pk_bf16_f32 v14, v14, v15
	v_cvt_pk_bf16_f32 v15, v16, v17
	v_mov_b32_e32 v158, v14
	v_mov_b32_e32 v159, v15
	global_load_dwordx4 v[14:17], v[36:37], off
	s_nop 0
	global_load_dwordx4 v[22:25], v[62:63], off
	v_lshl_add_u64 v[30:31], v[58:59], 0, v[42:43]
	global_load_dwordx4 v[26:29], v[30:31], off
	v_mul_f32_e32 v32, 0x4b800000, v52
	v_cndmask_b32_e32 v32, v52, v32, vcc
	v_rsq_f32_e32 v41, v32
	v_lshlrev_b64 v[32:33], 11, v[50:51]
	v_lshl_add_u64 v[32:33], v[38:39], 0, v[32:33]
	v_lshl_add_u64 v[50:51], v[60:61], 0, v[44:45]
	v_mul_f32_e32 v43, 0x45800000, v41
	v_cndmask_b32_e32 v52, v41, v43, vcc
	v_pk_mul_f32 v[18:19], v[18:19], v[52:53] op_sel_hi:[1,0]
	v_pk_mul_f32 v[20:21], v[20:21], v[52:53] op_sel_hi:[1,0]
	v_pk_mul_f32 v[10:11], v[10:11], v[52:53] op_sel_hi:[1,0]
	v_pk_mul_f32 v[12:13], v[12:13], v[52:53] op_sel_hi:[1,0]
	v_pk_mul_f32 v[6:7], v[6:7], v[52:53] op_sel_hi:[1,0]
	v_pk_mul_f32 v[8:9], v[8:9], v[52:53] op_sel_hi:[1,0]
	v_pk_mul_f32 v[2:3], v[2:3], v[52:53] op_sel_hi:[1,0]
	v_pk_mul_f32 v[4:5], v[4:5], v[52:53] op_sel_hi:[1,0]
	s_waitcnt vmcnt(2)
	v_pk_mul_f32 v[14:15], v[14:15], v[18:19]
	s_waitcnt vmcnt(1)
	v_pk_add_f32 v[18:19], v[22:23], 1.0 op_sel_hi:[1,0]
	v_pk_mul_f32 v[16:17], v[16:17], v[20:21]
	v_pk_add_f32 v[20:21], v[24:25], 1.0 op_sel_hi:[1,0]
	s_waitcnt vmcnt(0)
	v_pk_fma_f32 v[14:15], v[18:19], v[14:15], v[26:27]
	v_pk_fma_f32 v[16:17], v[16:17], v[20:21], v[28:29]
	v_cvt_pk_bf16_f32 v14, v14, v15
	v_cvt_pk_bf16_f32 v15, v16, v17
	v_mov_b32_e32 v160, v14
	v_mov_b32_e32 v161, v15
	global_load_dwordx4 v[14:17], v[36:37], off offset:1024
	s_nop 0
	global_load_dwordx4 v[18:21], v[50:51], off
	global_load_dwordx4 v[22:25], v[30:31], off offset:1024
	v_lshl_add_u64 v[26:27], v[60:61], 0, v[46:47]
	s_waitcnt vmcnt(2)
	v_pk_mul_f32 v[10:11], v[10:11], v[14:15]
	s_waitcnt vmcnt(1)
	v_pk_add_f32 v[14:15], v[18:19], 1.0 op_sel_hi:[1,0]
	v_pk_mul_f32 v[12:13], v[12:13], v[16:17]
	v_pk_add_f32 v[16:17], v[20:21], 1.0 op_sel_hi:[1,0]
	s_waitcnt vmcnt(0)
	v_pk_fma_f32 v[10:11], v[10:11], v[14:15], v[22:23]
	v_pk_fma_f32 v[12:13], v[12:13], v[16:17], v[24:25]
	v_cvt_pk_bf16_f32 v10, v10, v11
	v_cvt_pk_bf16_f32 v11, v12, v13
	v_mov_b32_e32 v162, v10
	v_mov_b32_e32 v163, v11
	global_load_dwordx4 v[10:13], v[36:37], off offset:2048
	s_nop 0
	global_load_dwordx4 v[14:17], v[26:27], off
	global_load_dwordx4 v[18:21], v[30:31], off offset:2048
	v_lshl_add_u64 v[22:23], v[60:61], 0, v[48:49]
	s_waitcnt vmcnt(2)
	v_pk_mul_f32 v[6:7], v[6:7], v[10:11]
	s_waitcnt vmcnt(1)
	v_pk_add_f32 v[10:11], v[14:15], 1.0 op_sel_hi:[1,0]
	v_pk_mul_f32 v[8:9], v[8:9], v[12:13]
	v_pk_add_f32 v[12:13], v[16:17], 1.0 op_sel_hi:[1,0]
	s_waitcnt vmcnt(0)
	v_pk_fma_f32 v[6:7], v[6:7], v[10:11], v[18:19]
	v_pk_fma_f32 v[8:9], v[8:9], v[12:13], v[20:21]
	v_cvt_pk_bf16_f32 v6, v6, v7
	v_cvt_pk_bf16_f32 v7, v8, v9
	v_mov_b32_e32 v164, v6
	v_mov_b32_e32 v165, v7
	global_load_dwordx4 v[6:9], v[36:37], off offset:3072
	s_nop 0
	global_load_dwordx4 v[10:13], v[22:23], off
	global_load_dwordx4 v[14:17], v[30:31], off offset:3072
	s_waitcnt vmcnt(2)
	v_pk_mul_f32 v[2:3], v[2:3], v[6:7]
	s_waitcnt vmcnt(1)
	v_pk_add_f32 v[6:7], v[10:11], 1.0 op_sel_hi:[1,0]
	v_pk_mul_f32 v[4:5], v[4:5], v[8:9]
	v_pk_add_f32 v[8:9], v[12:13], 1.0 op_sel_hi:[1,0]
	s_waitcnt vmcnt(0)
	v_pk_fma_f32 v[2:3], v[2:3], v[6:7], v[14:15]
	v_pk_fma_f32 v[4:5], v[4:5], v[8:9], v[16:17]
	v_cvt_pk_bf16_f32 v2, v2, v3
	v_cvt_pk_bf16_f32 v3, v4, v5
	v_mov_b32_e32 v166, v2
	v_mov_b32_e32 v167, v3
	global_store_dwordx2 v[76:77], v[152:153], off
	global_store_dwordx2 v[76:77], v[154:155], off offset:512
	global_store_dwordx2 v[76:77], v[156:157], off offset:1024
	global_store_dwordx2 v[76:77], v[158:159], off offset:1536
	global_store_dwordx2 v[32:33], v[160:161], off
	global_store_dwordx2 v[32:33], v[162:163], off offset:512
	global_store_dwordx2 v[32:33], v[164:165], off offset:1024
	global_store_dwordx2 v[32:33], v[166:167], off offset:1536
	s_cbranch_scc1 .LBB0_44

.LBB0_186:
	s_lshl_b32 s0, s10, 4
	s_and_b32 s11, s10, 3
	s_and_b32 s97, s0, 0xffffffc0
	s_cmpk_lt_i32 s97, 0x2000
	s_movk_i32 s1, 0xfc0
	s_cselect_b32 s1, 0xc0, s1
	v_mov_b32_e32 v1, v149
	s_cselect_b32 s54, 0x100, s7
	s_and_b32 s55, s1, s0
	s_mov_b32 s0, 0x2aaaaaab
	s_waitcnt lgkmcnt(0)
	s_barrier
	s_add_i32 s55, s55, -2
	v_mul_hi_i32 v34, v1, s0
	v_lshrrev_b32_e32 v38, 31, v34
	v_ashrrev_i32_e32 v2, 2, v34
	v_add_u32_e32 v32, v2, v38
	v_add_u32_e32 v2, s55, v32
	s_movk_i32 s0, 0x660
	v_cmp_gt_i32_e64 s[0:1], s0, v1
	v_cmp_gt_i32_e64 s[40:41], s54, v2
	v_cmp_lt_i32_e32 vcc, -1, v2
	s_and_b64 s[40:41], s[0:1], s[40:41]
	s_add_i32 s13, s97, -2
	s_lshl_b32 s12, s11, 6
	s_and_b64 s[42:43], s[40:41], vcc
	v_mov_b32_e32 v2, 0
	v_mov_b32_e32 v6, 0
	v_mov_b32_e32 v7, 0
	v_mov_b32_e32 v8, 0
	v_mov_b32_e32 v9, 0
	s_and_saveexec_b64 s[40:41], s[42:43]
	s_cbranch_execz .LBB0_188
	v_lshrrev_b32_e32 v3, 2, v34
	v_add_u32_e32 v3, v3, v38
	v_mul_lo_u32 v3, v3, 24
	v_sub_u32_e32 v3, v1, v3
	v_add_u32_e32 v6, s13, v32
	v_mov_b64_e32 v[4:5], s[34:35]
	v_mad_i64_i32 v[4:5], s[42:43], v6, s9, v[4:5]
	v_lshlrev_b32_e32 v6, 5, v3
	v_and_b32_e32 v6, 0xffffff00, v6
	v_ashrrev_i32_e32 v7, 31, v6
	v_lshl_add_u64 v[4:5], v[6:7], 1, v[4:5]
	s_lshl_b32 s2, s12, 1
	v_lshlrev_b32_e32 v3, 4, v3
	v_lshl_add_u64 v[4:5], v[4:5], 0, s[2:3]
	v_and_b32_e32 v6, 0x70, v3
	v_mov_b32_e32 v7, v0
	v_lshl_add_u64 v[4:5], v[4:5], 0, v[6:7]
	v_add_co_u32_e32 v4, vcc, 0x1000, v4
	s_nop 1
	v_addc_co_u32_e32 v5, vcc, 0, v5, vcc
	global_load_dwordx4 v[6:9], v[4:5], off

.LBB0_375:
	v_or_b32_e32 v1, s42, v193
	v_cmp_le_u32_e32 vcc, s43, v1
	s_lshl_b32 s2, s2, 6
	s_and_b32 s2, s2, 0x3c0
	s_and_saveexec_b64 s[12:13], vcc
	s_cbranch_execz .Lp0_inrange
	ds_write_b32 v232, v0
	ds_write_b32 v232, v0 offset:1040
	ds_write_b32 v232, v0 offset:2080
	ds_write_b32 v232, v0 offset:3120
	ds_write_b32 v232, v0 offset:4160
	ds_write_b32 v232, v0 offset:5200
	ds_write_b32 v232, v0 offset:6240
	ds_write_b32 v232, v0 offset:7280
	ds_write_b32 v232, v0 offset:8320
	ds_write_b32 v232, v0 offset:9360
	ds_write_b32 v232, v0 offset:10400
	ds_write_b32 v232, v0 offset:11440
	ds_write_b32 v232, v0 offset:12480
	ds_write_b32 v232, v0 offset:13520
	ds_write_b32 v232, v0 offset:14560
	ds_write_b32 v232, v0 offset:15600
.Lp0_inrange:
	s_andn2_b64 exec, s[12:13], exec
	s_cbranch_execz .Lp0_done
	v_add_u32_e32 v168, s2, v194
	v_mad_u32_u24 v168, v168, s43, v1
	v_mov_b32_e32 v169, v0
	v_lshl_add_u64 v[168:169], v[168:169], 2, s[10:11]
	global_load_dword v152, v[168:169], off
	v_add_u32_e32 v170, s2, v196
	v_mad_u32_u24 v170, v170, s43, v1
	v_mov_b32_e32 v171, v0
	v_lshl_add_u64 v[170:171], v[170:171], 2, s[10:11]
	global_load_dword v153, v[170:171], off
	v_add_u32_e32 v168, s2, v197
	v_mad_u32_u24 v168, v168, s43, v1
	v_mov_b32_e32 v169, v0
	v_lshl_add_u64 v[168:169], v[168:169], 2, s[10:11]
	global_load_dword v154, v[168:169], off
	v_add_u32_e32 v170, s2, v198
	v_mad_u32_u24 v170, v170, s43, v1
	v_mov_b32_e32 v171, v0
	v_lshl_add_u64 v[170:171], v[170:171], 2, s[10:11]
	global_load_dword v155, v[170:171], off
	v_add_u32_e32 v168, s2, v199
	v_mad_u32_u24 v168, v168, s43, v1
	v_mov_b32_e32 v169, v0
	v_lshl_add_u64 v[168:169], v[168:169], 2, s[10:11]
	global_load_dword v156, v[168:169], off
	v_add_u32_e32 v170, s2, v200
	v_mad_u32_u24 v170, v170, s43, v1
	v_mov_b32_e32 v171, v0
	v_lshl_add_u64 v[170:171], v[170:171], 2, s[10:11]
	global_load_dword v157, v[170:171], off
	v_add_u32_e32 v168, s2, v201
	v_mad_u32_u24 v168, v168, s43, v1
	v_mov_b32_e32 v169, v0
	v_lshl_add_u64 v[168:169], v[168:169], 2, s[10:11]
	global_load_dword v158, v[168:169], off
	v_add_u32_e32 v170, s2, v202
	v_mad_u32_u24 v170, v170, s43, v1
	v_mov_b32_e32 v171, v0
	v_lshl_add_u64 v[170:171], v[170:171], 2, s[10:11]
	global_load_dword v159, v[170:171], off
	v_add_u32_e32 v168, s2, v203
	v_mad_u32_u24 v168, v168, s43, v1
	v_mov_b32_e32 v169, v0
	v_lshl_add_u64 v[168:169], v[168:169], 2, s[10:11]
	global_load_dword v160, v[168:169], off
	v_add_u32_e32 v170, s2, v204
	v_mad_u32_u24 v170, v170, s43, v1
	v_mov_b32_e32 v171, v0
	v_lshl_add_u64 v[170:171], v[170:171], 2, s[10:11]
	global_load_dword v161, v[170:171], off
	v_add_u32_e32 v168, s2, v205
	v_mad_u32_u24 v168, v168, s43, v1
	v_mov_b32_e32 v169, v0
	v_lshl_add_u64 v[168:169], v[168:169], 2, s[10:11]
	global_load_dword v162, v[168:169], off
	v_add_u32_e32 v170, s2, v206
	v_mad_u32_u24 v170, v170, s43, v1
	v_mov_b32_e32 v171, v0
	v_lshl_add_u64 v[170:171], v[170:171], 2, s[10:11]
	global_load_dword v163, v[170:171], off
	v_add_u32_e32 v168, s2, v207
	v_mad_u32_u24 v168, v168, s43, v1
	v_mov_b32_e32 v169, v0
	v_lshl_add_u64 v[168:169], v[168:169], 2, s[10:11]
	global_load_dword v164, v[168:169], off
	v_add_u32_e32 v170, s2, v208
	v_mad_u32_u24 v170, v170, s43, v1
	v_mov_b32_e32 v171, v0
	v_lshl_add_u64 v[170:171], v[170:171], 2, s[10:11]
	global_load_dword v165, v[170:171], off
	v_add_u32_e32 v168, s2, v209
	v_mad_u32_u24 v168, v168, s43, v1
	v_mov_b32_e32 v169, v0
	v_lshl_add_u64 v[168:169], v[168:169], 2, s[10:11]
	global_load_dword v166, v[168:169], off
	v_add_u32_e32 v170, s2, v210
	v_mad_u32_u24 v170, v170, s43, v1
	v_mov_b32_e32 v171, v0
	v_lshl_add_u64 v[170:171], v[170:171], 2, s[10:11]
	global_load_dword v167, v[170:171], off
	s_waitcnt vmcnt(15)
	ds_write_b32 v232, v152
	s_waitcnt vmcnt(14)
	ds_write_b32 v232, v153 offset:1040
	s_waitcnt vmcnt(13)
	ds_write_b32 v232, v154 offset:2080
	s_waitcnt vmcnt(12)
	ds_write_b32 v232, v155 offset:3120
	s_waitcnt vmcnt(11)
	ds_write_b32 v232, v156 offset:4160
	s_waitcnt vmcnt(10)
	ds_write_b32 v232, v157 offset:5200
	s_waitcnt vmcnt(9)
	ds_write_b32 v232, v158 offset:6240
	s_waitcnt vmcnt(8)
	ds_write_b32 v232, v159 offset:7280
	s_waitcnt vmcnt(7)
	ds_write_b32 v232, v160 offset:8320
	s_waitcnt vmcnt(6)
	ds_write_b32 v232, v161 offset:9360
	s_waitcnt vmcnt(5)
	ds_write_b32 v232, v162 offset:10400
	s_waitcnt vmcnt(4)
	ds_write_b32 v232, v163 offset:11440
	s_waitcnt vmcnt(3)
	ds_write_b32 v232, v164 offset:12480
	s_waitcnt vmcnt(2)
	ds_write_b32 v232, v165 offset:13520
	s_waitcnt vmcnt(1)
	ds_write_b32 v232, v166 offset:14560
	s_waitcnt vmcnt(0)
	ds_write_b32 v232, v167 offset:15600
.Lp0_done:
	s_mov_b64 exec, s[12:13]
	s_waitcnt lgkmcnt(0)
	s_barrier
	ds_read2_b32 v[2:3], v211 offset1:4
	ds_read2_b32 v[4:5], v211 offset0:8 offset1:12
	s_waitcnt lgkmcnt(1)
	v_cvt_pk_bf16_f32 v1, v2, s0
	v_or_b32_e32 v2, s42, v194
	v_lshlrev_b32_e32 v2, 10, v2
	v_or3_b32 v2, v2, v193, s2
	v_lshlrev_b32_e32 v2, 1, v2
	global_store_short v2, v1, s[0:1]
	v_or_b32_e32 v2, s42, v196
	v_lshlrev_b32_e32 v2, 10, v2
	v_or3_b32 v2, v2, v193, s2
	v_cvt_pk_bf16_f32 v1, v3, s0
	v_lshlrev_b32_e32 v2, 1, v2
	global_store_short v2, v1, s[0:1]
	v_or_b32_e32 v2, s42, v197
	v_lshlrev_b32_e32 v2, 10, v2
	v_or3_b32 v2, v2, v193, s2
	s_waitcnt lgkmcnt(0)
	v_cvt_pk_bf16_f32 v1, v4, s0
	v_lshlrev_b32_e32 v2, 1, v2
	global_store_short v2, v1, s[0:1]
	ds_read2_b32 v[2:3], v211 offset0:16 offset1:20
	v_or_b32_e32 v4, s42, v198
	v_lshlrev_b32_e32 v4, 10, v4
	v_or3_b32 v4, v4, v193, s2
	v_cvt_pk_bf16_f32 v1, v5, s0
	v_lshlrev_b32_e32 v4, 1, v4
	global_store_short v4, v1, s[0:1]
	s_waitcnt lgkmcnt(0)
	v_cvt_pk_bf16_f32 v1, v2, s0
	v_or_b32_e32 v2, s42, v199
	v_lshlrev_b32_e32 v2, 10, v2
	v_or3_b32 v2, v2, v193, s2
	v_lshlrev_b32_e32 v2, 1, v2
	global_store_short v2, v1, s[0:1]
	v_cvt_pk_bf16_f32 v1, v3, s0
	ds_read2_b32 v[2:3], v211 offset0:24 offset1:28
	v_or_b32_e32 v4, s42, v200
	v_lshlrev_b32_e32 v4, 10, v4
	v_or3_b32 v4, v4, v193, s2
	v_lshlrev_b32_e32 v4, 1, v4
	global_store_short v4, v1, s[0:1]
	s_waitcnt lgkmcnt(0)
	v_cvt_pk_bf16_f32 v1, v2, s0
	v_or_b32_e32 v2, s42, v201
	v_lshlrev_b32_e32 v2, 10, v2
	v_or3_b32 v2, v2, v193, s2
	v_lshlrev_b32_e32 v2, 1, v2
	global_store_short v2, v1, s[0:1]
	v_cvt_pk_bf16_f32 v1, v3, s0
	ds_read2_b32 v[2:3], v211 offset0:32 offset1:36
	v_or_b32_e32 v4, s42, v202
	v_lshlrev_b32_e32 v4, 10, v4
	v_or3_b32 v4, v4, v193, s2
	v_lshlrev_b32_e32 v4, 1, v4
	global_store_short v4, v1, s[0:1]
	s_waitcnt lgkmcnt(0)
	v_cvt_pk_bf16_f32 v1, v2, s0
	v_or_b32_e32 v2, s42, v203
	v_lshlrev_b32_e32 v2, 10, v2
	v_or3_b32 v2, v2, v193, s2
	v_lshlrev_b32_e32 v2, 1, v2
	global_store_short v2, v1, s[0:1]
	v_cvt_pk_bf16_f32 v1, v3, s0
	ds_read2_b32 v[2:3], v211 offset0:40 offset1:44
	v_or_b32_e32 v4, s42, v204
	v_lshlrev_b32_e32 v4, 10, v4
	v_or3_b32 v4, v4, v193, s2
	v_lshlrev_b32_e32 v4, 1, v4
	global_store_short v4, v1, s[0:1]
	s_waitcnt lgkmcnt(0)
	v_cvt_pk_bf16_f32 v1, v2, s0
	v_or_b32_e32 v2, s42, v205
	v_lshlrev_b32_e32 v2, 10, v2
	v_or3_b32 v2, v2, v193, s2
	v_lshlrev_b32_e32 v2, 1, v2
	global_store_short v2, v1, s[0:1]
	v_cvt_pk_bf16_f32 v1, v3, s0
	ds_read2_b32 v[2:3], v211 offset0:48 offset1:52
	v_or_b32_e32 v4, s42, v206
	v_lshlrev_b32_e32 v4, 10, v4
	v_or3_b32 v4, v4, v193, s2
	v_lshlrev_b32_e32 v4, 1, v4
	global_store_short v4, v1, s[0:1]
	s_waitcnt lgkmcnt(0)
	v_cvt_pk_bf16_f32 v1, v2, s0
	v_or_b32_e32 v2, s42, v207
	v_lshlrev_b32_e32 v2, 10, v2
	v_or3_b32 v2, v2, v193, s2
	v_lshlrev_b32_e32 v2, 1, v2
	global_store_short v2, v1, s[0:1]
	v_cvt_pk_bf16_f32 v1, v3, s0
	ds_read2_b32 v[2:3], v211 offset0:56 offset1:60
	v_add_lshl_u32 v4, s42, v208, 10
	v_or3_b32 v4, v4, v193, s2
	v_lshlrev_b32_e32 v4, 1, v4
	global_store_short v4, v1, s[0:1]
	s_waitcnt lgkmcnt(0)
	v_cvt_pk_bf16_f32 v1, v2, s0
	v_add_lshl_u32 v2, s42, v209, 10
	v_or3_b32 v2, v2, v193, s2
	v_lshlrev_b32_e32 v2, 1, v2
	global_store_short v2, v1, s[0:1]
	v_add_lshl_u32 v2, s42, v210, 10
	v_or3_b32 v2, v2, v193, s2
	v_cvt_pk_bf16_f32 v1, v3, s0
	v_lshlrev_b32_e32 v2, 1, v2
	global_store_short v2, v1, s[0:1]
